# FFN-up under-filled last round runs on XCDs 0-3 only; workgroups on XCDs 4-7 convert 5 tiles each meanwhile (no L2 sharing between the GEMM round and the conversion stream)
# baseline (speedup 1.0000x reference)
; __global__ void __launch_bounds__(NWAVES * 64, 2) mega_fwd(Args A) {
;     ...
;     const int G = gridDim.x, bx = blockIdx.x;
;     unsigned char* ws = A.ws;
;     for (int u = tid; u < (LDS_BYTES - LDSCTL_OFF) / 4; u += NWAVES * 64) ((LAS unsigned*)(lds + LDSCTL_OFF))[u] = 0u;
;     __syncthreads();
;     XcdBarrier bar = xcd_barrier_post((unsigned*)(ws + WS_CTL) + CW_BAR, (volatile LAS unsigned*)(lds + MISC_OFF) + 8);
;     float* X = (float*)(ws + WS_X); bf16* H = (bf16*)(ws + WS_H); bf16* ACT = (bf16*)(ws + WS_ACT); bf16* PROJ = (bf16*)(ws + WS_PROJ);
;     bf16* Y = (bf16*)(ws + WS_Y); float* MACC = (float*)(ws + WS_MACC); bf16* MB = (bf16*)(ws + WS_MB); float* GO = (float*)(ws + WS_GO);
;     const float* COS = (const float*)(ws + WS_ROPE); const float* SIN = COS + (size_t)NTOK * 32;
;     { int t_ = threadIdx.x; asm volatile("" : "+v"(t_)); const int w_ = __builtin_amdgcn_readfirstlane(t_ >> 6); p0_prologue(A, lds, bx * NWAVES + w_, G * NWAVES, w_, t_ & 63); }
;     conv_until(A, lds, TL_WO1, 0);
;     xcd_barrier(bar);
; #pragma unroll 1
;     for (int step = 0; step < 3 * DEPTH; ++step) {
;         const int l = step / 3, kind = step - 3 * l;
;         unsigned char* wl = ws + WS_W + (size_t)l * LW_END;
;         const unsigned long long* ssq = (const unsigned long long*)(ws + WS_CTL + CTL_SSQ) + (size_t)step * NTOK; unsigned long long* ssq_next = (unsigned long long*)(ws + WS_CTL + CTL_SSQ) + (size_t)(step + 1) * NTOK;
;         if (kind != 1) {
;             { pg8::Gemm g{H, (const bf16*)(wl + (kind == 0 ? LW_WI1 : LW_WI2)), NTOK, NWI, DM}; pg8::StaticOrder S; S.init(NTOK, NWI, G, bx);
;               pg8::EpiSwiglu E{ACT, DFF, ssq};
;               pg8::gemm_phase<pg8::EpiSwiglu, pg8::StaticOrder, true, true>(lds + RING_OFF, g, S, E); }
;             { const int rem1 = ((NTOK / 256) * (NWI / 256)) % G;
;               conv_until(A, lds, l * TL_LAYER + (kind == 0 ? TL_WIN : TL_LAYER), (rem1 != 0 && bx >= rem1) ? 3 : 0); }
;             xcd_barrier(bar);
;         } else {
;             const bool std256 = (G == 256);
;             unsigned char* XB8 = ws + WS_X;
; #pragma unroll 1
;             for (int part = 0; part < 3; ++part) {
;                 bool do16, do8; int i16, n16, g8, c8, i8, n8;
;                 if (std256) { do16 = part == 0 || (part == 1 && bx < 64); i16 = part ? 2 : 0; n16 = part ? 1 : 2;
.LBB0_284:
	v_writelane_b32 v252, s64, 42
	s_nop 1
	v_writelane_b32 v252, s65, 43
	v_writelane_b32 v252, s66, 44
	v_writelane_b32 v252, s67, 45
	v_writelane_b32 v252, s68, 46
	v_writelane_b32 v252, s69, 47
	v_writelane_b32 v252, s70, 48
	v_writelane_b32 v252, s71, 49
	v_writelane_b32 v252, s72, 50
	v_writelane_b32 v252, s73, 51
	v_writelane_b32 v252, s74, 52
	v_writelane_b32 v252, s75, 53
	v_writelane_b32 v252, s76, 54
	v_writelane_b32 v252, s77, 55
	v_writelane_b32 v252, s78, 56
	v_writelane_b32 v252, s79, 57
	s_or_b64 exec, exec, s[0:1]
	s_cmpk_lg_i32 s95, 0x100
	s_cselect_b64 s[0:1], -1, 0
	s_and_b64 s[0:1], s[0:1], exec
	s_cselect_b32 s69, s95, 0x80
	s_add_i32 s4, s97, 0xffffff80
	s_cmpk_lg_i32 s95, 0x100
	s_cselect_b64 s[0:1], -1, 0
	s_and_b64 s[2:3], s[0:1], exec
	s_cselect_b32 s20, s97, s4
	v_readlane_b32 s4, v252, 2
	v_readlane_b32 s18, v252, 16
	v_readlane_b32 s19, v252, 17
	s_add_u32 s74, s18, 0x10000
	s_addc_u32 s2, s19, 0
	v_readlane_b32 s5, v252, 3
	v_readlane_b32 s6, v252, 4
	v_readlane_b32 s7, v252, 5
	v_readlane_b32 s8, v252, 6
	v_readlane_b32 s9, v252, 7
	v_readlane_b32 s10, v252, 8
	v_readlane_b32 s11, v252, 9
	v_readlane_b32 s12, v252, 10
	v_readlane_b32 s13, v252, 11
	v_readlane_b32 s14, v252, 12
	v_readlane_b32 s15, v252, 13
	v_readlane_b32 s16, v252, 14
	v_readlane_b32 s17, v252, 15
	v_writelane_b32 v252, s2, 58
	s_add_u32 s2, s18, 0x35e00000
	s_addc_u32 s3, s19, 0
	s_add_u32 s88, s18, 0x3b600000
	s_addc_u32 s89, s19, 0
	v_writelane_b32 v252, s2, 59
	s_add_u32 s12, s18, 0x45e00000
	s_addc_u32 s13, s19, 0
	v_writelane_b32 v252, s3, 60
	v_writelane_b32 v252, s12, 61
	s_add_u32 s2, s18, 0x4c200000
	v_writelane_b32 v252, s13, 62
	s_addc_u32 s3, s19, 0
	v_writelane_b32 v252, s2, 63
	s_waitcnt vmcnt(15)
	v_mov_b32_e32 v3, 0
	v_mov_b32_e32 v216, 1
	v_writelane_b32 v253, s3, 0
	s_add_u32 s2, s18, 0x4e200000
	s_addc_u32 s3, s19, 0
	v_writelane_b32 v253, s2, 1
	v_mov_b32_e32 v217, 0x7f7f7f7f
	v_mov_b32_e32 v225, 0x43e00000
	v_writelane_b32 v253, s3, 2
	s_add_u32 s2, s18, 0x4fa00000
	s_addc_u32 s3, s19, 0
	v_writelane_b32 v253, s2, 3
	v_mov_b64_e32 v[226:227], 0x2ff
	v_mov_b32_e32 v222, 0x41b17218
	v_writelane_b32 v253, s3, 4
	s_add_u32 s2, s18, 0x4fb00000
	s_addc_u32 s3, s19, 0
	v_writelane_b32 v253, s2, 5
	v_mbcnt_hi_u32_b32 v223, -1, v76
	v_mov_b32_e32 v224, 0xf149f2ca
	v_writelane_b32 v253, s3, 6
	s_add_u32 s2, s18, 0x200000
	v_writelane_b32 v253, s2, 7
	s_addc_u32 s2, s19, 0
	s_cmpk_lt_i32 s97, 0x580
	v_writelane_b32 v253, s2, 8
	s_cselect_b64 s[2:3], -1, 0
	v_writelane_b32 v253, s2, 9
	s_ashr_i32 s21, s97, 31
	s_movk_i32 s75, 0xc0
	v_writelane_b32 v253, s3, 10
	s_lshr_b32 s2, s21, 29
	s_add_i32 s3, s97, s2
	s_ashr_i32 s2, s3, 3
	s_and_b32 s3, s3, -8
	s_sub_i32 s5, s97, s3
	s_ashr_i32 s3, s95, 31
	s_add_u32 s6, s18, 0x4200
	v_writelane_b32 v253, s3, 11
	s_addc_u32 s7, s19, 0
	v_writelane_b32 v253, s6, 12
	s_movk_i32 s76, 0x300
	s_movk_i32 s77, 0x5400
	v_writelane_b32 v253, s7, 13
	s_add_u32 s6, s18, 0x4400
	s_addc_u32 s7, s19, 0
	v_writelane_b32 v253, s6, 14
	s_movk_i32 s81, 0x7fff
	s_mov_b32 s82, 0xffff0000
	v_writelane_b32 v253, s7, 15
	s_add_u32 s6, s18, 0x4500
	s_addc_u32 s7, s19, 0
	v_writelane_b32 v253, s6, 16
	s_movk_i32 s61, 0x1110
	s_movk_i32 s84, 0x15ff
	v_writelane_b32 v253, s7, 17
	s_add_u32 s6, s18, 0x4600
	s_addc_u32 s7, s19, 0
	v_writelane_b32 v253, s6, 18
	s_mov_b32 s85, 0xc3e00000
	s_movk_i32 s33, 0xff
	v_writelane_b32 v253, s7, 19
	s_add_u32 s6, s18, 0x4700
	s_addc_u32 s7, s19, 0
	v_writelane_b32 v253, s6, 20
	s_movk_i32 s66, 0x90
	s_mov_b32 s96, 0x2aaaaaab
	v_writelane_b32 v253, s7, 21
	s_add_u32 s6, s18, 0x4800
	s_addc_u32 s7, s19, 0
	v_writelane_b32 v253, s6, 22
	s_movk_i32 s36, 0x190
	s_movk_i32 s37, 0xff40
	v_writelane_b32 v253, s7, 23
	s_add_u32 s6, s18, 0x4900
	s_addc_u32 s7, s19, 0
	v_writelane_b32 v253, s6, 24
	s_movk_i32 s38, 0x567
	s_movk_i32 s39, 0x1500
	v_writelane_b32 v253, s7, 25
	s_add_u32 s6, s18, 0x4a00
	s_addc_u32 s7, s19, 0
	v_writelane_b32 v253, s6, 26
	s_movk_i32 s56, 0x1800
	s_movk_i32 s57, 0xc80
	v_writelane_b32 v253, s7, 27
	s_add_u32 s6, s18, 0x4b00
	s_addc_u32 s7, s19, 0
	v_writelane_b32 v253, s6, 28
	s_movk_i32 s58, 0x3ff
	s_mov_b32 s80, 0xefa18f08
	v_writelane_b32 v253, s7, 29
	s_add_u32 s6, s18, 0x4c00
	s_addc_u32 s7, s19, 0
	v_writelane_b32 v253, s6, 30
	s_mov_b32 s62, 0
	s_mov_b32 s94, 0x3e000000
	v_writelane_b32 v253, s7, 31
	s_add_u32 s6, s18, 0x4d00
	s_addc_u32 s7, s19, 0
	v_writelane_b32 v253, s6, 32
	s_waitcnt lgkmcnt(0)
	s_barrier
; __global__ void __launch_bounds__(NWAVES * 64, 2) mega_fwd(Args A) {
;     ...
;             const bool std256 = (G == 256);
;             unsigned char* XB8 = ws + WS_X;
; #pragma unroll 1
;             for (int part = 0; part < 3; ++part) {
;                 bool do16, do8; int i16, n16, g8, c8, i8, n8;
;                 if (std256) { do16 = part == 0 || (part == 1 && bx < 64); i16 = part ? 2 : 0; n16 = part ? 1 : 2;
;                               do8 = (part == 1 && bx >= 64) || (part == 2 && bx < 128); g8 = part == 1 ? 192 : 128; c8 = part == 1 ? bx - 64 : bx; i8 = part == 1 ? 0 : 3; n8 = part == 1 ? 2 : 3; }
;                 else { do16 = part == 0; i16 = 0; n16 = 1 << 20; do8 = part == 1; g8 = G; c8 = bx; i8 = 0; n8 = 1 << 20; }
;                 if (do16) { pg8::Gemm g{H, (const bf16*)(wl + LW_WIN), NTOK, C_GATE, DM}; pg8::RangeOrder S; S.init(NTOK, C_GATE, G, bx); S.i0 = i16; S.n = n16;
;                     pg8::EpiProj E{PROJ, NPROJ, (const float*)A.in[7] + (size_t)l * 6144, 1 << 20, ssq, 1.0f};
;                     pg8::gemm_phase<pg8::EpiProj, pg8::RangeOrder, true, true>(lds + RING_OFF, g, S, E); }
;                 if (do8) { pg8::Gemm g{(const bf16*)XB8, (const bf16*)(wl + LW_WIN + WIN8_OFF), NTOK, 6144, DM / 2}; pg8::RangeOrder S; S.init(NTOK, 6144, g8, c8); S.i0 = i8; S.n = n8;
;                     pg8::EpiGate8 E{(unsigned char*)(PROJ + C_GATE), NPROJ * 2, (const float*)A.in[7] + (size_t)l * 6144, ssq, 1.0f / 2048.0f};
;                     pg8::gemm_phase<pg8::EpiGate8, pg8::RangeOrder, true, true, true>(lds + RING_OFF, g, S, E); }
;                 if (part == 1) xcd_barrier(bar);
;                 if (part == 2 && (!std256 || bx >= 128)) { const int mb = std256 ? bx - 128 : bx, ms = std256 ? 128 : G;
;                     if ((ms & 3) == 0) pool_units(lds, PROJ, (const bf16*)(ws + WS_WPT) + (size_t)l * 4 * 192 * 192, Y + (size_t)NTOK * BRW, mb, ms, 512);
;                     else for (int u = mb; u < 512; u += ms) pool_units(lds, PROJ, (const bf16*)(ws + WS_WPT) + (size_t)l * 4 * 192 * 192, Y + (size_t)NTOK * BRW, u, 512, 512);
;                     gla_pre_items(lds, PROJ, (const float*)A.in[11] + (size_t)l * 16 * 384, (const float*)A.in[12] + l * 384, ws + WS_GPRE, mb, ms, 512); }
;             }
;             xcd_barrier(bar);
;             if (G > 96) { if (bx < 48) gla_scan_unit(lds, ws + WS_GPRE, GO, bx);
	v_writelane_b32 v253, s7, 33
	s_add_u32 s6, s18, 0x4e00
	s_addc_u32 s7, s19, 0
	v_writelane_b32 v253, s6, 34
	s_nop 1
	v_writelane_b32 v253, s7, 35
	s_add_u32 s6, s18, 0x4f00
	s_addc_u32 s7, s19, 0
	v_writelane_b32 v253, s6, 36
	s_nop 1
	v_writelane_b32 v253, s7, 37
	s_add_u32 s6, s18, 0x5000
	s_addc_u32 s7, s19, 0
	v_writelane_b32 v253, s6, 38
	s_nop 1
	v_writelane_b32 v253, s7, 39
	s_add_u32 s6, s18, 0x5100
	s_addc_u32 s7, s19, 0
	v_writelane_b32 v253, s6, 40
	s_nop 1
	v_writelane_b32 v253, s7, 41
	s_add_u32 s6, s18, 0x5200
	s_addc_u32 s7, s19, 0
	v_writelane_b32 v253, s6, 42
	s_nop 1
	v_writelane_b32 v253, s7, 43
	s_add_u32 s6, s18, 0x5300
	s_addc_u32 s7, s19, 0
	v_writelane_b32 v253, s6, 44
	s_nop 1
	v_writelane_b32 v253, s7, 45
	s_add_u32 s6, s18, 0x7400
	s_addc_u32 s7, s19, 0
	v_writelane_b32 v253, s6, 46
	s_nop 1
	v_writelane_b32 v253, s7, 47
	s_add_u32 s6, s18, 0x7500
	s_addc_u32 s7, s19, 0
	v_writelane_b32 v253, s6, 48
	s_cmpk_eq_i32 s95, 0x100
	s_nop 0
	v_writelane_b32 v253, s7, 49
	s_cselect_b64 s[6:7], -1, 0
	s_add_u32 s72, s18, 0x2fe00000
	s_addc_u32 s73, s19, 0
	v_writelane_b32 v253, s6, 50
	s_cmp_lt_i32 s97, 64
	s_nop 0
	v_writelane_b32 v253, s7, 51
	s_cselect_b64 s[6:7], -1, 0
	v_writelane_b32 v253, s6, 52
	s_cmp_gt_i32 s97, 63
	s_nop 0
	v_writelane_b32 v253, s7, 53
	s_cselect_b64 s[6:7], -1, 0
	v_writelane_b32 v253, s6, 54
	s_cmpk_lt_i32 s97, 0x80
	s_nop 0
	v_writelane_b32 v253, s7, 55
	s_cselect_b64 s[6:7], -1, 0
	v_writelane_b32 v253, s6, 56
	s_sub_i32 s3, s97, 64
	s_nop 0
	v_writelane_b32 v253, s7, 57
	s_add_u32 s6, s18, 0x3b602400
	v_writelane_b32 v253, s3, 58
	s_addc_u32 s7, s19, 0
	v_writelane_b32 v253, s6, 59
	s_cmpk_gt_i32 s97, 0x7f
	s_nop 0
	v_writelane_b32 v253, s7, 60
	s_cselect_b64 s[6:7], -1, 0
	s_or_b64 s[0:1], s[6:7], s[0:1]
	v_writelane_b32 v253, s0, 61
	s_nop 1
	v_writelane_b32 v253, s1, 62
	s_and_b32 s0, s69, 3
	s_cmp_lg_u32 s0, 0
	s_cselect_b64 s[0:1], -1, 0
	v_writelane_b32 v253, s0, 63
	s_cmpk_lt_i32 s20, 0x200
	s_nop 0
	v_writelane_b32 v254, s1, 0
	s_cselect_b64 s[0:1], -1, 0
	v_writelane_b32 v254, s0, 1
	s_nop 1
	v_writelane_b32 v254, s1, 2
	s_add_u32 s0, s18, 0x46a00000
	s_addc_u32 s1, s19, 0
	v_writelane_b32 v254, s0, 3
	s_and_b32 s4, s20, 3
	s_nop 0
	v_writelane_b32 v254, s1, 4
	s_mul_i32 s0, s4, 0x12000
	s_add_u32 s0, s34, s0
	v_writelane_b32 v254, s0, 5
	v_writelane_b32 v254, s34, 6
	s_addc_u32 s0, s35, 0
	s_lshl_b32 s68, 2, s4
	v_writelane_b32 v254, s35, 7
	v_writelane_b32 v254, s0, 8
	s_lshl_b32 s1, s20, 4
	s_lshl_b32 s0, s69, 4
	s_add_u32 s22, s18, 0x4fc00000
	v_writelane_b32 v254, s0, 9
	s_addc_u32 s23, s19, 0
	s_lshl_b32 s0, s20, 6
	s_and_b32 s0, s0, 0x7c0
	v_writelane_b32 v254, s1, 10
	s_and_b32 s1, s1, 0xfffff800
	s_or_b32 s0, s1, s0
	s_ashr_i32 s1, s0, 31
	v_writelane_b32 v254, s0, 11
	s_bfe_u32 s3, s20, 0x20005
	s_mov_b32 s35, 0
	v_writelane_b32 v254, s1, 12
	s_mul_i32 s0, s3, 0x60
	v_writelane_b32 v254, s20, 13
	s_add_i32 s1, s0, 0x920
	v_writelane_b32 v254, s1, 14
	v_writelane_b32 v254, s0, 15
	s_bitset1_b32 s0, 11
	s_cmpk_lt_i32 s95, 0x61
	v_writelane_b32 v254, s0, 16
	s_cselect_b64 s[0:1], -1, 0
	s_cmpk_gt_i32 s95, 0x60
	v_writelane_b32 v254, s0, 17
	s_cselect_b64 s[6:7], -1, 0
	s_cmp_lt_i32 s97, 48
	v_writelane_b32 v254, s1, 18
	s_cselect_b64 s[0:1], -1, 0
	v_writelane_b32 v254, s0, 19
	s_cmpk_lt_i32 s97, 0x100
	s_nop 0
	v_writelane_b32 v254, s1, 20
	s_cselect_b64 s[0:1], -1, 0
	v_writelane_b32 v254, s0, 21
	s_nop 1
	v_writelane_b32 v254, s1, 22
	s_sub_i32 s0, s97, 48
	v_writelane_b32 v254, s0, 23
	s_cmpk_lt_i32 s97, 0x130
	s_mul_hi_i32 s0, s97, 0x55555556
	s_cselect_b64 s[8:9], -1, 0
	s_lshr_b32 s1, s0, 31
	s_add_i32 s10, s0, s1
	s_mul_i32 s0, s10, -3
	s_add_i32 s0, s0, s97
	v_writelane_b32 v254, s8, 24
	s_lshl_b32 s1, s0, 13
	s_add_i32 s1, s1, 0x8000
	v_writelane_b32 v254, s9, 25
	v_writelane_b32 v254, s1, 26
	s_sub_i32 s1, s95, 48
	v_writelane_b32 v254, s1, 27
	s_lshl_b32 s8, s10, 5
	s_mul_i32 s1, s10, 0x1c4000
	v_writelane_b32 v254, s8, 28
	s_mul_hi_i32 s8, s8, 0xe200
	s_add_u32 s14, s22, s1
	s_addc_u32 s15, s23, s8
	s_add_u32 s8, s14, 0xe000
	v_writelane_b32 v254, s14, 29
	s_addc_u32 s9, s15, 0
	s_lshl_b32 s1, s10, 9
	s_lshl_b32 s0, s0, 6
	v_writelane_b32 v254, s15, 30
	s_and_b32 s11, s1, 0xfffff800
	s_ashr_i32 s1, s0, 31
	v_writelane_b32 v254, s8, 31
	s_cmp_gt_i32 s97, 47
	s_nop 0
	v_writelane_b32 v254, s9, 32
	s_cselect_b64 s[8:9], -1, 0
	v_writelane_b32 v254, s8, 33
	s_mov_b64 s[14:15], s[6:7]
	s_add_i32 s6, s97, s95
	s_addk_i32 s6, 0xffa0
	v_writelane_b32 v254, s9, 34
	s_cmpk_lt_i32 s6, 0x100
	s_cselect_b32 s8, 2, 4
	v_writelane_b32 v254, s14, 35
	s_and_b64 s[6:7], s[14:15], exec
	s_cselect_b32 s6, s8, 0
	v_writelane_b32 v254, s15, 36
	v_writelane_b32 v254, s6, 37
	s_add_u32 s6, s18, 0x47600000
	v_writelane_b32 v254, s6, 38
	s_addc_u32 s6, s19, 0
	v_writelane_b32 v254, s6, 39
	s_lshl_b32 s14, s95, 5
	s_lshl_b32 s6, s5, 5
	s_cmp_lt_i32 s5, 0
	s_movk_i32 s7, 0xb1
	s_cselect_b32 s7, s7, 0xb0
; __global__ void __launch_bounds__(NWAVES * 64, 2) mega_fwd(Args A) {
;     ...
;             { const int rem1 = ((NTOK / 256) * (NWI / 256)) % G;
;               conv_until(A, lds, l * TL_LAYER + (kind == 0 ? TL_WIN : TL_LAYER), (rem1 != 0 && bx >= rem1) ? 3 : 0); }
	s_mul_i32 s7, s5, s7
	s_mul_i32 s5, s5, 33
	s_cselect_b32 s5, s5, s6
	s_add_i32 s7, s7, s2
	s_mul_hi_i32 s6, s7, 0x2e8ba2e9
	s_lshr_b32 s8, s6, 31
	s_ashr_i32 s6, s6, 6
	s_add_i32 s6, s6, s8
	s_mul_i32 s8, s6, 0x160
	s_sub_i32 s7, s7, s8
	s_bfe_u32 s8, s7, 0x3001c
	s_add_i32 s8, s7, s8
	s_and_b32 s9, s8, 0xfff8
	s_sub_i32 s7, s7, s9
	s_lshl_b32 s6, s6, 3
	s_sext_i32_i16 s8, s8
	s_sext_i32_i16 s7, s7
	s_add_i32 s16, s6, s7
	s_ashr_i32 s6, s8, 3
	v_writelane_b32 v254, s6, 40
	s_lshr_b32 s6, s8, 3
	s_bfe_i64 s[6:7], s[6:7], 0x100000
	s_lshl_b64 s[6:7], s[6:7], 20
	v_writelane_b32 v254, s6, 41
	s_ashr_i32 s17, s16, 31
	s_nop 0
	v_writelane_b32 v254, s7, 42
	s_mov_b32 s6, s16
	v_writelane_b32 v254, s6, 43
	s_nop 1
	v_writelane_b32 v254, s7, 44
	s_lshl_b64 s[6:7], s[16:17], 20
	s_add_u32 s6, s90, s6
	s_addc_u32 s7, s91, s7
	s_add_u32 s8, s6, 0x80000
	s_addc_u32 s9, s7, 0
	v_writelane_b32 v254, s8, 45
	s_nop 1
	v_writelane_b32 v254, s9, 46
	s_add_u32 s8, s6, 0x2000
	v_writelane_b32 v254, s6, 47
	s_addc_u32 s9, s7, 0
	s_add_i32 s2, s5, s2
	s_ashr_i32 s5, s2, 31
	s_lshr_b32 s5, s5, 26
	s_add_i32 s5, s2, s5
	v_writelane_b32 v254, s7, 48
	s_and_b32 s6, s5, 0xffc0
	s_sub_i32 s2, s2, s6
	s_bfe_i32 s6, s2, 0x80000
	s_bfe_u32 s6, s6, 0x3000c
	s_add_i32 s6, s2, s6
	s_and_b32 s7, s6, 0xf8
	s_sub_i32 s2, s2, s7
	s_ashr_i32 s5, s5, 6
	s_lshl_b32 s5, s5, 3
	s_sext_i32_i8 s2, s2
	s_add_i32 s5, s5, s2
	s_bfe_i32 s2, s6, 0x80000
	v_writelane_b32 v254, s8, 49
	s_sext_i32_i16 s2, s2
	s_ashr_i32 s6, s2, 3
	v_writelane_b32 v254, s9, 50
	s_lshr_b32 s2, s2, 3
	v_writelane_b32 v254, s6, 51
	s_bfe_i64 s[6:7], s[2:3], 0x100000
	v_writelane_b32 v254, s6, 52
	s_mul_hi_i32 s2, s5, 0x60000
	s_nop 0
	v_writelane_b32 v254, s7, 53
	v_writelane_b32 v254, s5, 54
	s_mul_i32 s5, s5, 0x60000
	s_add_u32 s6, s12, s5
	s_addc_u32 s7, s13, s2
	s_add_u32 s8, s6, 0x30000
	s_addc_u32 s9, s7, 0
	v_writelane_b32 v254, s8, 55
	s_nop 1
	v_writelane_b32 v254, s9, 56
	s_add_u32 s8, s6, 0x2000
	v_writelane_b32 v254, s6, 57
	s_addc_u32 s9, s7, 0
	s_abs_i32 s2, s95
	v_cvt_f32_u32_e32 v1, s2
	v_writelane_b32 v254, s7, 58
	s_sub_i32 s5, 0, s2
	v_writelane_b32 v254, s8, 59
	v_rcp_iflag_f32_e32 v1, v1
	s_nop 0
	v_writelane_b32 v254, s9, 60
	v_mul_f32_e32 v1, 0x4f7ffffe, v1
	v_cvt_u32_f32_e32 v1, v1
	s_nop 0
	v_readfirstlane_b32 s6, v1
	s_mul_i32 s5, s5, s6
	s_mul_hi_u32 s5, s6, s5
	s_add_i32 s6, s6, s5
	s_mul_hi_u32 s5, s6, 0x580
	s_mul_i32 s5, s5, s2
	s_sub_i32 s5, 0x580, s5
	s_sub_i32 s6, s5, s2
	s_cmp_ge_u32 s5, s2
	s_cselect_b32 s5, s6, s5
	s_sub_i32 s6, s5, s2
	s_cmp_ge_u32 s5, s2
	s_cselect_b32 s2, s6, s5
	s_cmp_lg_u32 s2, 0
	s_cselect_b64 s[6:7], -1, 0
	s_and_b32 s5, s97, 7
	s_cmp_ge_u32 s5, 4
	s_cselect_b64 s[8:9], -1, 0
	s_and_b64 s[6:7], s[6:7], s[8:9]
	s_mul_i32 s2, s4, 0xc0
	v_writelane_b32 v254, s6, 61
	s_and_b64 s[4:5], s[6:7], exec
	s_cselect_b32 s4, 5, 0
	v_writelane_b32 v254, s7, 62
	v_writelane_b32 v255, s2, 0
	s_lshl_b32 s2, s2, 1
	v_writelane_b32 v254, s4, 63
	s_add_u32 s4, s88, s2
	s_addc_u32 s5, s89, 0
	v_writelane_b32 v255, s4, 1
	s_and_b32 s2, s10, 3
	s_mulk_i32 s2, 0x300
	v_writelane_b32 v255, s5, 2
	s_mul_i32 s4, s11, 0xc00
	s_lshl_b32 s5, s97, 6
	s_or_b32 s2, s4, s2
	s_lshl_b64 s[0:1], s[0:1], 2
	v_writelane_b32 v255, s5, 3
	s_lshl_b32 s5, s95, 6
	s_mul_hi_i32 s4, s11, 0xc00
	s_add_u32 s0, s2, s0
	s_addc_u32 s1, s4, s1
	s_add_u32 s0, s18, s0
	v_writelane_b32 v255, s5, 4
	s_addc_u32 s1, s19, s1
	v_writelane_b32 v255, s0, 5
	s_mul_i32 s2, s95, 0x18000
	s_add_i32 s93, 0, 0x20180
	v_writelane_b32 v255, s1, 6
	s_mul_i32 s0, s3, 0xc0
	s_mul_hi_i32 s3, s14, 0xc00
	v_writelane_b32 v255, s2, 7
	s_lshl_b32 s1, s97, 9
	s_lshl_b32 s0, s0, 1
	v_writelane_b32 v255, s3, 8
	s_mul_i32 s2, s95, 0xa8000
	v_writelane_b32 v255, s14, 9
	s_mul_hi_i32 s3, s14, 0x5400
	v_writelane_b32 v255, s2, 10
	s_add_i32 s60, 0, 0x20184
	v_mov_b32_e32 v1, 0x358637bd
	v_writelane_b32 v255, s3, 11
	v_writelane_b32 v255, s1, 12
	s_lshl_b32 s1, s95, 11
	v_writelane_b32 v255, s1, 13
	s_lshl_b32 s1, s95, 4
	v_writelane_b32 v255, s1, 14
	s_lshl_b32 s1, s95, 10
	v_writelane_b32 v255, s1, 15
	s_lshl_b32 s1, s95, 9
	v_writelane_b32 v255, s1, 16
	s_add_i32 s1, 0, 0x20160
	v_writelane_b32 v255, s1, 17
	s_add_i32 s1, 0, 0x20164
	v_writelane_b32 v255, s1, 18
	s_add_i32 s1, 0, 0x2d00
	v_writelane_b32 v255, s1, 19
	v_writelane_b32 v255, s0, 20
	s_add_i32 s64, 0, 0x12600
	s_nop 0
	v_writelane_b32 v255, s1, 21
	s_add_i32 s0, 0, 0xf000
	v_writelane_b32 v255, s0, 22
	s_add_i32 s0, 0, 0x8800
	v_writelane_b32 v255, s0, 23
	v_writelane_b32 v255, s90, 24
	s_nop 1
	v_writelane_b32 v255, s91, 25
	v_writelane_b32 v255, s69, 26
	v_writelane_b32 v255, s88, 27
	s_nop 1
	v_writelane_b32 v255, s89, 28
	v_writelane_b32 v255, s21, 29
	v_writelane_b32 v255, s22, 30
	v_writelane_b32 v255, s23, 31
	v_writelane_b32 v255, s93, 32
	v_writelane_b32 v255, s60, 33
	v_writelane_b32 v255, s92, 34
	s_nop 1
	v_writelane_b32 v255, s93, 35
	s_branch .LBB0_287

;     __host__ __device__ bool next(int i, Unit& u) const {
;         const long L = (long)i * G + c; if (L >= nwg) return false;
;         int wgid = (int)L; { const int q = nwg / NXCD, r = nwg % NXCD, xcd = wgid % NXCD, off = wgid / NXCD; wgid = (xcd < r ? xcd * (q + 1) : r * (q + 1) + (xcd - r) * q) + off; }
;         const int nig = WGM * nN, gid = wgid / nig, fm = gid * WGM, gsz = (nM - fm) < WGM ? (nM - fm) : WGM;
;         u.pm = fm + ((wgid % nig) % gsz); u.pn = (wgid % nig) / gsz; u.seg = 0; return true;
; __global__ void __launch_bounds__(NWAVES * 64, 2) mega_fwd(Args A) {
;     ...
;         if (kind != 1) {
;             { pg8::Gemm g{H, (const bf16*)(wl + (kind == 0 ? LW_WI1 : LW_WI2)), NTOK, NWI, DM}; pg8::StaticOrder S; S.init(NTOK, NWI, G, bx);
;               pg8::EpiSwiglu E{ACT, DFF, ssq};
;               pg8::gemm_phase<pg8::EpiSwiglu, pg8::StaticOrder, true, true>(lds + RING_OFF, g, S, E); }
.LBB0_294:
	s_add_i32 s53, s53, 1
	v_readlane_b32 s2, v253, 11
	s_mul_i32 s2, s53, s2
	s_mul_hi_u32 s3, s53, s95
	s_add_i32 s3, s3, s2
	s_mul_i32 s2, s53, s95
	s_add_u32 s12, s2, s97
	v_readlane_b32 s2, v255, 29
	s_addc_u32 s13, s3, s2
	s_cmp_lg_u32 s53, 5
	s_cbranch_scc1 .Lr6_skip
	s_and_b32 s21, s97, 7
	s_lshr_b32 s22, s97, 3
	s_lshr_b32 s23, s22, 1
	s_lshl_b32 s23, s23, 3
	s_and_b32 s22, s22, 1
	s_lshl_b32 s22, s22, 2
	s_add_i32 s23, s23, s22
	s_add_i32 s23, s23, s21
	s_cmp_lt_u32 s21, 4
	s_cselect_b32 s23, s23, 0x80
	s_add_i32 s12, s23, 0x500
	s_mov_b32 s13, 0
.Lr6_skip:
	v_mov_b64_e32 v[4:5], 0x580
	v_cmp_lt_i64_e64 s[2:3], s[12:13], v[4:5]
	v_mov_b64_e32 v[4:5], 0x57f
	v_cmp_gt_i64_e32 vcc, s[12:13], v[4:5]
	s_cbranch_vccnz .LBB0_296
	s_ashr_i32 s8, s12, 31
	s_lshr_b32 s8, s8, 29
	s_add_i32 s8, s12, s8
	s_ashr_i32 s9, s8, 3
	s_and_b32 s8, s8, -8
	s_sub_i32 s8, s12, s8
	s_cmp_lt_i32 s8, 0
	s_movk_i32 s10, 0xb1
	s_cselect_b32 s10, s10, 0xb0
	s_mul_i32 s8, s8, s10
	s_add_i32 s8, s8, s9
	s_mul_hi_i32 s9, s8, 0x2e8ba2e9
	s_lshr_b32 s10, s9, 31
	s_ashr_i32 s9, s9, 6
	s_add_i32 s9, s9, s10
	s_lshl_b32 s10, s9, 3
	s_sub_i32 s11, 32, s10
	s_min_i32 s11, s11, 8
	s_abs_i32 s12, s11
	v_cvt_f32_u32_e32 v4, s12
	s_sub_i32 s14, 0, s12
	s_mulk_i32 s9, 0x160
	s_sub_i32 s9, s8, s9
	v_rcp_iflag_f32_e32 v4, v4
	s_abs_i32 s8, s9
	s_xor_b32 s13, s9, s11
	s_ashr_i32 s13, s13, 31
	v_mul_f32_e32 v4, 0x4f7ffffe, v4
	v_cvt_u32_f32_e32 v4, v4
	s_nop 0
	v_readfirstlane_b32 s15, v4
	s_mul_i32 s14, s14, s15
	s_mul_hi_u32 s14, s15, s14
	s_add_i32 s15, s15, s14
	s_mul_hi_u32 s14, s8, s15
	s_mul_i32 s15, s14, s12
	s_sub_i32 s8, s8, s15
	s_add_i32 s20, s14, 1
	s_sub_i32 s15, s8, s12
	s_cmp_ge_u32 s8, s12
	s_cselect_b32 s14, s20, s14
	s_cselect_b32 s8, s15, s8
	s_add_i32 s15, s14, 1
	s_cmp_ge_u32 s8, s12
	s_cselect_b32 s8, s15, s14
	s_xor_b32 s8, s8, s13
	s_sub_i32 s8, s8, s13
	s_mul_i32 s11, s8, s11
	s_sub_i32 s9, s9, s11
	s_add_i32 s10, s10, s9
